# speedup vs baseline: 1.0089x; 1.0089x over previous
; #define LAS __attribute__((address_space(3)))
; #define MFMA32(a_, b_, c_) __builtin_amdgcn_mfma_f32_32x32x16_bf16((a_), (b_), (c_), 0, 0, 0)
; __device__ __forceinline__ int crow(int reg, int h) { return (reg & 3) + 8 * (reg >> 2) + 4 * h; }
; #define WAVE_FENCE() asm volatile("s_waitcnt lgkmcnt(0)" ::: "memory")
; template <bool OUT>
; __device__ __forceinline__ void ssm_fast(KArgs ap, int l, LAS unsigned char* lds, const Ctx cx) {
;     ...
;         for (int sc = 0; sc < 4; ++sc) {
;             const size_t tk = tok0 + sc * 32;
;             const bf16x8 uf = *(const bf16x8*)(z + (tk + r) * DIN + ZS + g * 16 + 8 * hh);
;             bf16_t uv[2][4];
;             if (OUT) {
; #pragma unroll
;                 for (int tbk = 0; tbk < 2; ++tbk)
; #pragma unroll
;                     for (int j = 0; j < 4; ++j) uv[tbk][j] = z[(tk + tbk * 16 + 4 * (lane >> 4) + j) * DIN + ZS + g * 16 + (lane & 15)];
;             }
;             WAVE_FENCE();
; #pragma unroll
;             for (int nb = 0; nb < 4; ++nb) { f32x16 c;
; #pragma unroll
;                 for (int i = 0; i < 16; ++i) c[i] = 0.f;
;                 c = MFMA32(uf, bt[nb], c);
; #pragma unroll
;                 for (int i = 0; i < 16; ++i) *(LAS float*)(BU + (crow(i, hh) * 128 + nb * 32 + r) * 4) = c[i]; }
;             WAVE_FENCE();
; #pragma unroll 4
;             for (int t = 0; t < 32; ++t) {
;                 const float br = *(const LAS float*)(BU + (t * 128 + p) * 4), bi = *(const LAS float*)(BU + (t * 128 + 64 + p) * 4);
;                 const float nr = are * sr - aim * si + br, ni = are * si + aim * sr + bi; sr = nr; si = ni;
.LBB0_170:
	s_lshl_b32 s76, s5, 5
	v_lshl_add_u64 v[0:1], v[90:91], 0, s[76:77]
	v_mov_b64_e32 v[2:3], s[0:1]
	s_movk_i32 s7, 0x1600
	v_mad_u64_u32 v[2:3], s[10:11], v0, s7, v[2:3]
	v_mad_i32_i24 v3, v1, s7, v3
	s_mov_b32 s7, s77
	v_lshl_add_u64 v[0:1], v[2:3], 0, s[6:7]
	v_lshl_add_u64 v[0:1], v[84:85], 1, v[0:1]
	v_add_co_u32_e32 v0, vcc, 0x13000000, v0
	v_add_u32_e32 v95, 0x400, v87
	s_nop 0
	v_addc_co_u32_e32 v1, vcc, 0, v1, vcc
	global_load_dwordx4 v[48:51], v[0:1], off offset:2560
	v_add_u32_e32 v96, 0x1000, v87
	v_add_u32_e32 v97, 0x1400, v87
	v_add_u32_e32 v98, 0x2000, v87
	v_add_u32_e32 v99, 0x2400, v87
	v_add_u32_e32 v100, 0x3000, v87
	v_add_u32_e32 v101, 0x3400, v87
	s_waitcnt lgkmcnt(0)
	s_mov_b32 s7, 0
	s_waitcnt vmcnt(0)
	v_mfma_f32_32x32x16_bf16 v[0:15], v[48:51], v[64:67], 0
	v_mfma_f32_32x32x16_bf16 v[16:31], v[48:51], v[68:71], 0
	v_mfma_f32_32x32x16_bf16 v[32:47], v[48:51], v[72:75], 0
	v_mfma_f32_32x32x16_bf16 v[48:63], v[48:51], v[76:79], 0
	s_nop 9
	s_waitcnt lgkmcnt(0)
.LBB0_171:
	v_permlane32_swap_b32_e32 v0, v16
	v_permlane32_swap_b32_e32 v1, v17
	v_permlane32_swap_b32_e32 v2, v18
	v_permlane32_swap_b32_e32 v3, v19
	v_permlane32_swap_b32_e32 v4, v20
	v_permlane32_swap_b32_e32 v5, v21
	v_permlane32_swap_b32_e32 v6, v22
	v_permlane32_swap_b32_e32 v7, v23
	v_permlane32_swap_b32_e32 v8, v24
	v_permlane32_swap_b32_e32 v9, v25
	v_permlane32_swap_b32_e32 v10, v26
	v_permlane32_swap_b32_e32 v11, v27
	v_permlane32_swap_b32_e32 v12, v28
	v_permlane32_swap_b32_e32 v13, v29
	v_permlane32_swap_b32_e32 v14, v30
	v_permlane32_swap_b32_e32 v15, v31
	v_permlane32_swap_b32_e32 v32, v48
	v_permlane32_swap_b32_e32 v33, v49
	v_permlane32_swap_b32_e32 v34, v50
	v_permlane32_swap_b32_e32 v35, v51
	v_permlane32_swap_b32_e32 v36, v52
	v_permlane32_swap_b32_e32 v37, v53
	v_permlane32_swap_b32_e32 v38, v54
	v_permlane32_swap_b32_e32 v39, v55
	v_permlane32_swap_b32_e32 v40, v56
	v_permlane32_swap_b32_e32 v41, v57
	v_permlane32_swap_b32_e32 v42, v58
	v_permlane32_swap_b32_e32 v43, v59
	v_permlane32_swap_b32_e32 v44, v60
	v_permlane32_swap_b32_e32 v45, v61
	v_permlane32_swap_b32_e32 v46, v62
	v_permlane32_swap_b32_e32 v47, v63
	v_mul_f32_e32 v113, v81, v93
	v_mul_f32_e32 v115, v80, v93
	v_fma_f32 v114, v80, v92, -v113
	v_fma_f32 v116, v81, v92, v115
	v_add_f32_e32 v92, v114, v0
	v_add_f32_e32 v93, v116, v32
	v_mul_f32_e32 v113, v81, v93
	v_mul_f32_e32 v115, v80, v93
	v_fma_f32 v114, v80, v92, -v113
	v_fma_f32 v116, v81, v92, v115
	v_add_f32_e32 v92, v114, v1
	v_add_f32_e32 v93, v116, v33
	v_mul_f32_e32 v113, v81, v93
	v_mul_f32_e32 v115, v80, v93
	v_fma_f32 v114, v80, v92, -v113
	v_fma_f32 v116, v81, v92, v115
	v_add_f32_e32 v92, v114, v2
	v_add_f32_e32 v93, v116, v34
	v_mul_f32_e32 v113, v81, v93
	v_mul_f32_e32 v115, v80, v93
	v_fma_f32 v114, v80, v92, -v113
	v_fma_f32 v116, v81, v92, v115
	v_add_f32_e32 v92, v114, v3
	v_add_f32_e32 v93, v116, v35
	v_mul_f32_e32 v113, v81, v93
	v_mul_f32_e32 v115, v80, v93
	v_fma_f32 v114, v80, v92, -v113
	v_fma_f32 v116, v81, v92, v115
	v_add_f32_e32 v92, v114, v16
	v_add_f32_e32 v93, v116, v48
	v_mul_f32_e32 v113, v81, v93
	v_mul_f32_e32 v115, v80, v93
	v_fma_f32 v114, v80, v92, -v113
	v_fma_f32 v116, v81, v92, v115
	v_add_f32_e32 v92, v114, v17
	v_add_f32_e32 v93, v116, v49
	v_mul_f32_e32 v113, v81, v93
	v_mul_f32_e32 v115, v80, v93
	v_fma_f32 v114, v80, v92, -v113
	v_fma_f32 v116, v81, v92, v115
	v_add_f32_e32 v92, v114, v18
	v_add_f32_e32 v93, v116, v50
	v_mul_f32_e32 v113, v81, v93
	v_mul_f32_e32 v115, v80, v93
	v_fma_f32 v114, v80, v92, -v113
	v_fma_f32 v116, v81, v92, v115
	v_add_f32_e32 v92, v114, v19
	v_add_f32_e32 v93, v116, v51
	v_mul_f32_e32 v113, v81, v93
	v_mul_f32_e32 v115, v80, v93
	v_fma_f32 v114, v80, v92, -v113
	v_fma_f32 v116, v81, v92, v115
	v_add_f32_e32 v92, v114, v4
	v_add_f32_e32 v93, v116, v36
	v_mul_f32_e32 v113, v81, v93
	v_mul_f32_e32 v115, v80, v93
	v_fma_f32 v114, v80, v92, -v113
	v_fma_f32 v116, v81, v92, v115
	v_add_f32_e32 v92, v114, v5
	v_add_f32_e32 v93, v116, v37
	v_mul_f32_e32 v113, v81, v93
	v_mul_f32_e32 v115, v80, v93
	v_fma_f32 v114, v80, v92, -v113
	v_fma_f32 v116, v81, v92, v115
	v_add_f32_e32 v92, v114, v6
	v_add_f32_e32 v93, v116, v38
; #define LAS __attribute__((address_space(3)))
; template <bool OUT>
; __device__ __forceinline__ void ssm_fast(KArgs ap, int l, LAS unsigned char* lds, const Ctx cx) {
;     ...
; #pragma unroll 4
;             for (int t = 0; t < 32; ++t) {
;                 const float br = *(const LAS float*)(BU + (t * 128 + p) * 4), bi = *(const LAS float*)(BU + (t * 128 + 64 + p) * 4);
;                 const float nr = are * sr - aim * si + br, ni = are * si + aim * sr + bi; sr = nr; si = ni;
;     ...
;         if (!OUT) { E[(size_t)it * 128 + p] = sr; E[(size_t)it * 128 + 64 + p] = si; }
	v_mul_f32_e32 v113, v81, v93
	v_mul_f32_e32 v115, v80, v93
	v_fma_f32 v114, v80, v92, -v113
	v_fma_f32 v116, v81, v92, v115
	v_add_f32_e32 v92, v114, v7
	v_add_f32_e32 v93, v116, v39
	v_mul_f32_e32 v113, v81, v93
	v_mul_f32_e32 v115, v80, v93
	v_fma_f32 v114, v80, v92, -v113
	v_fma_f32 v116, v81, v92, v115
	v_add_f32_e32 v92, v114, v20
	v_add_f32_e32 v93, v116, v52
	v_mul_f32_e32 v113, v81, v93
	v_mul_f32_e32 v115, v80, v93
	v_fma_f32 v114, v80, v92, -v113
	v_fma_f32 v116, v81, v92, v115
	v_add_f32_e32 v92, v114, v21
	v_add_f32_e32 v93, v116, v53
	v_mul_f32_e32 v113, v81, v93
	v_mul_f32_e32 v115, v80, v93
	v_fma_f32 v114, v80, v92, -v113
	v_fma_f32 v116, v81, v92, v115
	v_add_f32_e32 v92, v114, v22
	v_add_f32_e32 v93, v116, v54
	v_mul_f32_e32 v113, v81, v93
	v_mul_f32_e32 v115, v80, v93
	v_fma_f32 v114, v80, v92, -v113
	v_fma_f32 v116, v81, v92, v115
	v_add_f32_e32 v92, v114, v23
	v_add_f32_e32 v93, v116, v55
	v_mul_f32_e32 v113, v81, v93
	v_mul_f32_e32 v115, v80, v93
	v_fma_f32 v114, v80, v92, -v113
	v_fma_f32 v116, v81, v92, v115
	v_add_f32_e32 v92, v114, v8
	v_add_f32_e32 v93, v116, v40
	v_mul_f32_e32 v113, v81, v93
	v_mul_f32_e32 v115, v80, v93
	v_fma_f32 v114, v80, v92, -v113
	v_fma_f32 v116, v81, v92, v115
	v_add_f32_e32 v92, v114, v9
	v_add_f32_e32 v93, v116, v41
	v_mul_f32_e32 v113, v81, v93
	v_mul_f32_e32 v115, v80, v93
	v_fma_f32 v114, v80, v92, -v113
	v_fma_f32 v116, v81, v92, v115
	v_add_f32_e32 v92, v114, v10
	v_add_f32_e32 v93, v116, v42
	v_mul_f32_e32 v113, v81, v93
	v_mul_f32_e32 v115, v80, v93
	v_fma_f32 v114, v80, v92, -v113
	v_fma_f32 v116, v81, v92, v115
	v_add_f32_e32 v92, v114, v11
	v_add_f32_e32 v93, v116, v43
	v_mul_f32_e32 v113, v81, v93
	v_mul_f32_e32 v115, v80, v93
	v_fma_f32 v114, v80, v92, -v113
	v_fma_f32 v116, v81, v92, v115
	v_add_f32_e32 v92, v114, v24
	v_add_f32_e32 v93, v116, v56
	v_mul_f32_e32 v113, v81, v93
	v_mul_f32_e32 v115, v80, v93
	v_fma_f32 v114, v80, v92, -v113
	v_fma_f32 v116, v81, v92, v115
	v_add_f32_e32 v92, v114, v25
	v_add_f32_e32 v93, v116, v57
	v_mul_f32_e32 v113, v81, v93
	v_mul_f32_e32 v115, v80, v93
	v_fma_f32 v114, v80, v92, -v113
	v_fma_f32 v116, v81, v92, v115
	v_add_f32_e32 v92, v114, v26
	v_add_f32_e32 v93, v116, v58
	v_mul_f32_e32 v113, v81, v93
	v_mul_f32_e32 v115, v80, v93
	v_fma_f32 v114, v80, v92, -v113
	v_fma_f32 v116, v81, v92, v115
	v_add_f32_e32 v92, v114, v27
	v_add_f32_e32 v93, v116, v59
	v_mul_f32_e32 v113, v81, v93
	v_mul_f32_e32 v115, v80, v93
	v_fma_f32 v114, v80, v92, -v113
	v_fma_f32 v116, v81, v92, v115
	v_add_f32_e32 v92, v114, v12
	v_add_f32_e32 v93, v116, v44
	v_mul_f32_e32 v113, v81, v93
	v_mul_f32_e32 v115, v80, v93
	v_fma_f32 v114, v80, v92, -v113
	v_fma_f32 v116, v81, v92, v115
	v_add_f32_e32 v92, v114, v13
	v_add_f32_e32 v93, v116, v45
	v_mul_f32_e32 v113, v81, v93
	v_mul_f32_e32 v115, v80, v93
	v_fma_f32 v114, v80, v92, -v113
	v_fma_f32 v116, v81, v92, v115
	v_add_f32_e32 v92, v114, v14
	v_add_f32_e32 v93, v116, v46
	v_mul_f32_e32 v113, v81, v93
	v_mul_f32_e32 v115, v80, v93
	v_fma_f32 v114, v80, v92, -v113
	v_fma_f32 v116, v81, v92, v115
	v_add_f32_e32 v92, v114, v15
	v_add_f32_e32 v93, v116, v47
	v_mul_f32_e32 v113, v81, v93
	v_mul_f32_e32 v115, v80, v93
	v_fma_f32 v114, v80, v92, -v113
	v_fma_f32 v116, v81, v92, v115
	v_add_f32_e32 v92, v114, v28
	v_add_f32_e32 v93, v116, v60
	v_mul_f32_e32 v113, v81, v93
	v_mul_f32_e32 v115, v80, v93
	v_fma_f32 v114, v80, v92, -v113
	v_fma_f32 v116, v81, v92, v115
	v_add_f32_e32 v92, v114, v29
	v_add_f32_e32 v93, v116, v61
	v_mul_f32_e32 v113, v81, v93
	v_mul_f32_e32 v115, v80, v93
	v_fma_f32 v114, v80, v92, -v113
	v_fma_f32 v116, v81, v92, v115
	v_add_f32_e32 v92, v114, v30
	v_add_f32_e32 v93, v116, v62
	v_mul_f32_e32 v113, v81, v93
	v_mul_f32_e32 v115, v80, v93
	v_fma_f32 v114, v80, v92, -v113
	v_fma_f32 v116, v81, v92, v115
	v_add_f32_e32 v92, v114, v31
	v_add_f32_e32 v93, v116, v63
	s_add_i32 s5, s5, 1
	s_cmp_eq_u32 s5, 4
	s_cbranch_scc0 .LBB0_170
	s_ashr_i32 s5, s4, 31
	s_lshl_b64 s[10:11], s[4:5], 9
	s_add_i32 s4, s4, s8
	v_lshl_add_u64 v[0:1], v[82:83], 0, s[10:11]
	s_cmpk_gt_i32 s4, 0x1fff
	global_store_dword v[0:1], v92, off
	global_store_dword v[0:1], v93, off offset:256
	s_cbranch_scc0 .LBB0_169

; #define LAS __attribute__((address_space(3)))
; __device__ __forceinline__ unsigned f2bf(float f) { unsigned u = __builtin_bit_cast(unsigned, f); return (u + 0x7fffu + ((u >> 16) & 1u)) >> 16; }
; #define a (*get_args())
; template <bool OUT>
; __device__ __forceinline__ void ssm_fast(KArgs ap, int l, LAS unsigned char* lds, const Ctx cx) {
;     const int wave = cx.wave, lane = cx.lane;
;     const auto& a = *ap;
;     const bf16_t* z = (const bf16_t*)(a.ws + WS_Z); bf16_t* ypre = (bf16_t*)(a.ws + WS_YPRE); float* E = (float*)(a.ws + WS_E);
;     const unsigned char* tb = a.ws + WS_TAB + (size_t)l * TAB_STRIDE;
;     const int gw = cx.bid * 8 + wave, NGW = cx.nb * 8;
;     const int g = gw & 31, r = lane & 31, hh = lane >> 5, p = lane;
;     LAS unsigned char* BU = lds + wave * 16384;
;     const float are = ((const float*)(tb + TAB_A))[(g * 64 + p) * 2], aim = ((const float*)(tb + TAB_A))[(g * 64 + p) * 2 + 1];
;     bf16x8 bt[4];
; #pragma unroll
;     for (int nb = 0; nb < 4; ++nb) bt[nb] = *(const bf16x8*)((const bf16_t*)(tb + TAB_BT) + (g * 128 + nb * 32 + r) * 16 + 8 * hh);
;     bf16x8 ct[4]; float dsk = 0.f;
;     if (OUT) {
; #pragma unroll
;         for (int ks = 0; ks < 4; ++ks) ct[ks] = *(const bf16x8*)((const bf16_t*)(tb + TAB_CT) + (g * 16 + (lane & 15)) * 128 + ks * 32 + 8 * (lane >> 4));
;         dsk = a.in[I_SSM_D][l * 512 + g * 16 + (lane & 15)];
;     }
;     __syncthreads();
; #pragma unroll 1
;     for (int it = gw; it < BATCH * SSM_NC * 32; it += NGW) {
;         const size_t tok0 = (size_t)(it >> 5) * 128;
;         float sr = 0.f, si = 0.f;
;         if (OUT) { sr = E[(size_t)it * 128 + p]; si = E[(size_t)it * 128 + 64 + p]; }
; #pragma unroll 1
;         for (int sc = 0; sc < 4; ++sc) {
;             const size_t tk = tok0 + sc * 32;
;             const bf16x8 uf = *(const bf16x8*)(z + (tk + r) * DIN + ZS + g * 16 + 8 * hh);
;     ...
;                     *(LAS bf16_t*)(BU + t * 512 + ((((p >> 3)) ^ (t & 15)) << 4) + (p & 7) * 2) = (bf16_t)f2bf(sr);
;                     *(LAS bf16_t*)(BU + t * 512 + (((8 + (p >> 3)) ^ (t & 15)) << 4) + (p & 7) * 2) = (bf16_t)f2bf(si); }
.LBB0_305:
.LBB0_306:
	s_mov_b64 s[0:1], s[78:79]
	s_load_dword s0, s[0:1], 0xe0
	v_readlane_b32 s1, v243, 18
	s_add_i32 s56, s1, 6
	s_waitcnt lgkmcnt(0)
	s_cmp_gt_i32 s0, s55
	s_cbranch_scc1 .LBB0_376
	s_mov_b64 s[0:1], s[78:79]
	s_load_dword s0, s[0:1], 0xe4
	s_waitcnt lgkmcnt(0)
	s_cmp_ge_i32 s55, s0
	s_cbranch_scc1 .LBB0_376
	v_readlane_b32 s4, v243, 5
	v_mov_b32_e32 v8, v192
	v_readlane_b32 s0, v243, 0
	v_readlane_b32 s5, v243, 6
	s_load_dword s6, s[4:5], 0x0
	v_readfirstlane_b32 s1, v8
	s_ashr_i32 s8, s1, 6
	s_lshl_b32 s0, s0, 3
	s_add_i32 s0, s8, s0
	s_waitcnt lgkmcnt(0)
	s_mov_b32 s7, s6
	s_mov_b64 s[10:11], s[78:79]
	v_and_b32_e32 v2, 63, v8
	s_and_b32 s9, s0, 31
	s_load_dwordx2 s[4:5], s[10:11], 0xd8
	v_and_b32_e32 v96, 31, v8
	s_lshl_b32 s1, s9, 7
	v_lshlrev_b32_e32 v3, 1, v2
	v_or_b32_e32 v4, s1, v3
	v_or_b32_e32 v6, s1, v96
	s_lshl_b32 s1, s9, 4
	v_readlane_b32 s12, v243, 21
	s_or_b32 s12, s1, s12
	v_and_b32_e32 v0, 15, v8
	v_or_b32_e32 v152, s12, v0
	v_readlane_b32 s12, v243, 19
	v_readlane_b32 s13, v243, 22
	s_waitcnt lgkmcnt(0)
	s_add_u32 s12, s4, s12
	s_addc_u32 s13, s5, 0
	v_bfe_u32 v1, v8, 5, 1
	s_add_u32 s12, s12, 0x3e600000
	s_addc_u32 s13, s13, 0
	v_lshlrev_b32_e32 v9, 2, v4
	v_lshlrev_b32_e32 v4, 4, v1
	v_mov_b32_e32 v5, v153
	v_lshl_add_u64 v[4:5], s[12:13], 0, v[4:5]
	v_lshlrev_b32_e32 v6, 5, v6
	v_mov_b32_e32 v7, v153
	v_lshl_add_u64 v[4:5], v[4:5], 0, v[6:7]
	s_mov_b64 s[14:15], 0x8000
	v_lshl_add_u64 v[6:7], v[4:5], 0, s[14:15]
	s_load_dwordx2 s[10:11], s[10:11], 0x58
	global_load_dwordx2 v[98:99], v9, s[12:13]
	global_load_dwordx4 v[64:67], v[6:7], off offset:1024
	global_load_dwordx4 v[68:71], v[6:7], off offset:2048
	global_load_dwordx4 v[72:75], v[6:7], off offset:3072
	v_lshlrev_b32_e32 v6, 8, v8
	v_and_b32_e32 v6, 0xf00, v6
	s_mov_b32 s14, 0x8000
	v_lshl_or_b32 v6, s9, 12, v6
	v_mov_b32_e32 v7, v153
	v_add_co_u32_e32 v4, vcc, s14, v4
	v_lshl_add_u64 v[6:7], s[12:13], 0, v[6:7]
	v_and_b32_e32 v8, 48, v8
	v_mov_b32_e32 v9, v153
	v_addc_co_u32_e32 v5, vcc, 0, v5, vcc
	v_lshl_add_u64 v[6:7], v[6:7], 0, v[8:9]
	s_mov_b64 s[12:13], 0x28000
	v_lshl_add_u64 v[8:9], v[6:7], 0, s[12:13]
	v_add_co_u32_e32 v6, vcc, 0x28000, v6
	s_cmpk_gt_i32 s0, 0x1fff
	s_nop 0
	v_addc_co_u32_e32 v7, vcc, 0, v7, vcc
	global_load_dwordx4 v[76:79], v[6:7], off
	global_load_dwordx4 v[80:83], v[4:5], off
	global_load_dwordx4 v[84:87], v[8:9], off offset:64
	global_load_dwordx4 v[88:91], v[8:9], off offset:128
	global_load_dwordx4 v[92:95], v[8:9], off offset:192
	s_waitcnt lgkmcnt(0)
	v_lshl_add_u64 v[4:5], v[152:153], 2, s[10:11]
	global_load_dword v97, v[4:5], off
	s_waitcnt vmcnt(0)
	s_barrier
	s_cbranch_scc1 .LBB0_315
	s_lshl_b32 s8, s8, 14
	v_lshlrev_b32_e32 v4, 3, v1
	s_add_i32 s10, s8, 0
	v_lshrrev_b32_e32 v5, 2, v2
	v_lshlrev_b32_e32 v152, 2, v2
	v_lshrrev_b32_e32 v103, 3, v2
	v_and_b32_e32 v6, 14, v3
	v_lshrrev_b32_e32 v2, 4, v2
	v_lshlrev_b32_e32 v1, 11, v1
	v_lshlrev_b32_e32 v3, 2, v96
	v_add3_u32 v107, s10, v1, v3
	v_xor_b32_e32 v1, v2, v0
	v_and_b32_e32 v100, 12, v5
	v_or_b32_e32 v110, 3, v5
	v_or_b32_e32 v118, 19, v5
	v_lshlrev_b32_e32 v5, 4, v1
	v_bitop3_b32 v1, v2, v0, 4 bitop3:0x36
	v_lshlrev_b32_e32 v8, 4, v1
	v_bitop3_b32 v1, v2, v0, 8 bitop3:0x36
	s_lshl_b32 s7, s7, 3
	v_lshlrev_b32_e32 v102, 2, v2
	v_lshlrev_b32_e32 v9, 4, v1
	v_bitop3_b32 v1, v2, v0, 12 bitop3:0x36
	v_lshl_add_u64 v[2:3], s[4:5], 0, v[152:153]
	s_mov_b64 s[8:9], 0x3e000000
	s_lshl_b32 s1, s1, 1
	v_lshl_add_u64 v[132:133], v[2:3], 0, s[8:9]
	s_add_u32 s8, s4, s1
	s_addc_u32 s9, s5, 0
	s_add_u32 s1, s4, s1
	v_add_u32_e32 v101, s10, v152
	v_lshlrev_b32_e32 v152, 1, v0
	s_addc_u32 s5, s5, 0
	v_lshl_add_u32 v7, v0, 9, s10
	v_lshlrev_b32_e32 v10, 4, v1
	v_lshl_add_u64 v[0:1], s[8:9], 0, v[152:153]
	s_mov_b64 s[8:9], 0x3c000000
	s_add_u32 s4, s1, 0x13000000
	v_lshl_add_u64 v[134:135], v[0:1], 0, s[8:9]
	s_addc_u32 s5, s5, 0
	v_lshlrev_b32_e32 v0, 1, v4
	v_mov_b32_e32 v1, v153
	v_or_b32_e32 v105, 8, v103
	v_or_b32_e32 v104, 16, v102
	v_or_b32_e32 v106, 1, v100
	v_or_b32_e32 v108, 2, v100
	v_or_b32_e32 v112, 16, v100
	v_or_b32_e32 v114, 17, v100
	v_or_b32_e32 v116, 18, v100
	v_or_b32_e32 v120, 1, v102
	v_or_b32_e32 v122, 2, v102
	v_or_b32_e32 v124, 3, v102
	v_or_b32_e32 v126, 17, v102
	v_or_b32_e32 v128, 18, v102
	v_or_b32_e32 v130, 19, v102
	v_pk_mov_b32 v[136:137], v[98:99], v[98:99] op_sel:[1,0]
	v_lshl_add_u64 v[138:139], s[4:5], 0, v[0:1]
	v_lshl_add_u64 v[140:141], s[4:5], 0, v[152:153]
	v_add_u32_e32 v109, s10, v6
	v_add_u32_e32 v111, v7, v5
	v_add_u32_e32 v113, v7, v8
	v_add_u32_e32 v115, v7, v9
	v_add_u32_e32 v117, v7, v10
	v_xor_b32_e32 v215, 0, v103
	v_lshl_add_u32 v199, v215, 4, v109
	v_xor_b32_e32 v215, 1, v103
	v_lshl_add_u32 v200, v215, 4, v109
	v_xor_b32_e32 v215, 2, v103
	v_lshl_add_u32 v201, v215, 4, v109
	v_xor_b32_e32 v215, 3, v103
	v_lshl_add_u32 v202, v215, 4, v109
	v_xor_b32_e32 v215, 4, v103
	v_lshl_add_u32 v203, v215, 4, v109
	v_xor_b32_e32 v215, 5, v103
	v_lshl_add_u32 v204, v215, 4, v109
	v_xor_b32_e32 v215, 6, v103
	v_lshl_add_u32 v205, v215, 4, v109
	v_xor_b32_e32 v215, 7, v103
	v_lshl_add_u32 v206, v215, 4, v109
	v_xor_b32_e32 v215, 8, v103
	v_lshl_add_u32 v207, v215, 4, v109
	v_xor_b32_e32 v215, 9, v103
	v_lshl_add_u32 v208, v215, 4, v109
	v_xor_b32_e32 v215, 10, v103
	v_lshl_add_u32 v209, v215, 4, v109
	v_xor_b32_e32 v215, 11, v103
	v_lshl_add_u32 v210, v215, 4, v109
	v_xor_b32_e32 v215, 12, v103
	v_lshl_add_u32 v211, v215, 4, v109
	v_xor_b32_e32 v215, 13, v103
	v_lshl_add_u32 v212, v215, 4, v109
	v_xor_b32_e32 v215, 14, v103
	v_lshl_add_u32 v213, v215, 4, v109
	v_xor_b32_e32 v215, 15, v103
	v_lshl_add_u32 v214, v215, 4, v109

; #define LAS __attribute__((address_space(3)))
; __device__ __forceinline__ unsigned f2bf(float f) { unsigned u = __builtin_bit_cast(unsigned, f); return (u + 0x7fffu + ((u >> 16) & 1u)) >> 16; }
; #define MFMA32(a_, b_, c_) __builtin_amdgcn_mfma_f32_32x32x16_bf16((a_), (b_), (c_), 0, 0, 0)
; __device__ __forceinline__ int crow(int reg, int h) { return (reg & 3) + 8 * (reg >> 2) + 4 * h; }
; #define WAVE_FENCE() asm volatile("s_waitcnt lgkmcnt(0)" ::: "memory")
; template <bool OUT>
; __device__ __forceinline__ void ssm_fast(KArgs ap, int l, LAS unsigned char* lds, const Ctx cx) {
;     ...
;             const size_t tk = tok0 + sc * 32;
;             const bf16x8 uf = *(const bf16x8*)(z + (tk + r) * DIN + ZS + g * 16 + 8 * hh);
;             bf16_t uv[2][4];
;             if (OUT) {
; #pragma unroll
;                 for (int tbk = 0; tbk < 2; ++tbk)
; #pragma unroll
;                     for (int j = 0; j < 4; ++j) uv[tbk][j] = z[(tk + tbk * 16 + 4 * (lane >> 4) + j) * DIN + ZS + g * 16 + (lane & 15)];
;             }
;             WAVE_FENCE();
; #pragma unroll
;             for (int nb = 0; nb < 4; ++nb) { f32x16 c;
; #pragma unroll
;                 for (int i = 0; i < 16; ++i) c[i] = 0.f;
;                 c = MFMA32(uf, bt[nb], c);
; #pragma unroll
;                 for (int i = 0; i < 16; ++i) *(LAS float*)(BU + (crow(i, hh) * 128 + nb * 32 + r) * 4) = c[i]; }
;             WAVE_FENCE();
; #pragma unroll 4
;             for (int t = 0; t < 32; ++t) {
;                 const float br = *(const LAS float*)(BU + (t * 128 + p) * 4), bi = *(const LAS float*)(BU + (t * 128 + 64 + p) * 4);
;                 const float nr = are * sr - aim * si + br, ni = are * si + aim * sr + bi; sr = nr; si = ni;
;                 if (OUT) { asm volatile("" ::: "memory");
;                     *(LAS bf16_t*)(BU + t * 512 + ((((p >> 3)) ^ (t & 15)) << 4) + (p & 7) * 2) = (bf16_t)f2bf(sr);
;                     *(LAS bf16_t*)(BU + t * 512 + (((8 + (p >> 3)) ^ (t & 15)) << 4) + (p & 7) * 2) = (bf16_t)f2bf(si); }
.LBB0_311:
	s_lshl_b32 s8, s1, 5
	s_add_u32 s8, s4, s8
	v_or_b32_e32 v0, s8, v96
	s_movk_i32 s12, 0x1600
	s_addc_u32 s9, s5, 0
	v_mad_u64_u32 v[0:1], s[10:11], v0, s12, v[138:139]
	v_mad_i32_i24 v1, s9, v198, v1
	global_load_dwordx4 v[48:51], v[0:1], off offset:2560
	v_or_b32_e32 v0, s8, v100
	v_or_b32_e32 v1, s8, v106
	v_or_b32_e32 v2, s8, v108
	v_or_b32_e32 v3, s8, v110
	v_or_b32_e32 v4, s8, v112
	v_or_b32_e32 v5, s8, v114
	v_or_b32_e32 v6, s8, v116
	v_or_b32_e32 v7, s8, v118
	v_mad_u64_u32 v[32:33], s[10:11], v0, s12, v[140:141]
	v_mad_u64_u32 v[34:35], s[10:11], v1, s12, v[140:141]
	v_mad_u64_u32 v[36:37], s[10:11], v2, s12, v[140:141]
	v_mad_u64_u32 v[38:39], s[10:11], v3, s12, v[140:141]
	v_mad_u64_u32 v[40:41], s[10:11], v4, s12, v[140:141]
	v_mad_u64_u32 v[42:43], s[10:11], v5, s12, v[140:141]
	v_mad_u64_u32 v[44:45], s[10:11], v6, s12, v[140:141]
	v_mad_u64_u32 v[46:47], s[10:11], v7, s12, v[140:141]
	v_mad_i32_i24 v33, s9, v198, v33
	v_mad_i32_i24 v35, s9, v198, v35
	v_mad_i32_i24 v37, s9, v198, v37
	v_mad_i32_i24 v39, s9, v198, v39
	v_mad_i32_i24 v41, s9, v198, v41
	v_mad_i32_i24 v43, s9, v198, v43
	v_mad_i32_i24 v45, s9, v198, v45
	v_mad_i32_i24 v47, s9, v198, v47
	global_load_ushort v144, v[32:33], off offset:2560
	global_load_ushort v131, v[34:35], off offset:2560
	global_load_ushort v129, v[36:37], off offset:2560
	global_load_ushort v127, v[38:39], off offset:2560
	global_load_ushort v125, v[40:41], off offset:2560
	global_load_ushort v123, v[42:43], off offset:2560
	global_load_ushort v121, v[44:45], off offset:2560
	global_load_ushort v119, v[46:47], off offset:2560
	v_add_u32_e32 v145, 0x400, v107
	v_add_u32_e32 v146, 0x1000, v107
	v_add_u32_e32 v147, 0x1400, v107
	v_add_u32_e32 v148, 0x2000, v107
	v_add_u32_e32 v149, 0x2400, v107
	v_add_u32_e32 v150, 0x3000, v107
	v_add_u32_e32 v151, 0x3400, v107
	s_waitcnt lgkmcnt(0)
	s_movk_i32 s10, 0xc000
	s_mov_b32 s11, 3
	s_waitcnt vmcnt(8)
	v_mfma_f32_32x32x16_bf16 v[0:15], v[48:51], v[80:83], 0
	v_mfma_f32_32x32x16_bf16 v[16:31], v[48:51], v[64:67], 0
	v_mfma_f32_32x32x16_bf16 v[32:47], v[48:51], v[68:71], 0
	v_mfma_f32_32x32x16_bf16 v[48:63], v[48:51], v[72:75], 0
	s_nop 9
	s_waitcnt lgkmcnt(0)
.LBB0_312:
	v_permlane32_swap_b32_e32 v0, v16
	v_permlane32_swap_b32_e32 v1, v17
	v_permlane32_swap_b32_e32 v2, v18
	v_permlane32_swap_b32_e32 v3, v19
	v_permlane32_swap_b32_e32 v4, v20
	v_permlane32_swap_b32_e32 v5, v21
	v_permlane32_swap_b32_e32 v6, v22
	v_permlane32_swap_b32_e32 v7, v23
	v_permlane32_swap_b32_e32 v8, v24
	v_permlane32_swap_b32_e32 v9, v25
	v_permlane32_swap_b32_e32 v10, v26
	v_permlane32_swap_b32_e32 v11, v27
	v_permlane32_swap_b32_e32 v12, v28
	v_permlane32_swap_b32_e32 v13, v29
	v_permlane32_swap_b32_e32 v14, v30
	v_permlane32_swap_b32_e32 v15, v31
	v_permlane32_swap_b32_e32 v32, v48
	v_permlane32_swap_b32_e32 v33, v49
	v_permlane32_swap_b32_e32 v34, v50
	v_permlane32_swap_b32_e32 v35, v51
	v_permlane32_swap_b32_e32 v36, v52
	v_permlane32_swap_b32_e32 v37, v53
	v_permlane32_swap_b32_e32 v38, v54
	v_permlane32_swap_b32_e32 v39, v55
	v_permlane32_swap_b32_e32 v40, v56
	v_permlane32_swap_b32_e32 v41, v57
	v_permlane32_swap_b32_e32 v42, v58
	v_permlane32_swap_b32_e32 v43, v59
	v_permlane32_swap_b32_e32 v44, v60
	v_permlane32_swap_b32_e32 v45, v61
	v_permlane32_swap_b32_e32 v46, v62
	v_permlane32_swap_b32_e32 v47, v63
	v_mul_f32_e32 v176, v99, v143
	v_mul_f32_e32 v178, v98, v143
	v_fma_f32 v177, v98, v142, -v176
	v_fma_f32 v179, v99, v142, v178
	v_add_f32_e32 v142, v177, v0
	v_add_f32_e32 v143, v179, v32
	v_cvt_pk_bf16_f32 v184, v142, v143
	ds_write_b16 v199, v184 offset:0
	ds_write_b16_d16_hi v207, v184 offset:0
	v_mul_f32_e32 v176, v99, v143
	v_mul_f32_e32 v178, v98, v143
	v_fma_f32 v177, v98, v142, -v176
	v_fma_f32 v179, v99, v142, v178
	v_add_f32_e32 v142, v177, v1
	v_add_f32_e32 v143, v179, v33
	v_cvt_pk_bf16_f32 v185, v142, v143
	ds_write_b16 v200, v185 offset:512
	ds_write_b16_d16_hi v208, v185 offset:512
	v_mul_f32_e32 v176, v99, v143
	v_mul_f32_e32 v178, v98, v143
	v_fma_f32 v177, v98, v142, -v176
	v_fma_f32 v179, v99, v142, v178
	v_add_f32_e32 v142, v177, v2
	v_add_f32_e32 v143, v179, v34
	v_cvt_pk_bf16_f32 v186, v142, v143
	ds_write_b16 v201, v186 offset:1024
	ds_write_b16_d16_hi v209, v186 offset:1024
	v_mul_f32_e32 v176, v99, v143
	v_mul_f32_e32 v178, v98, v143
	v_fma_f32 v177, v98, v142, -v176
	v_fma_f32 v179, v99, v142, v178
	v_add_f32_e32 v142, v177, v3
	v_add_f32_e32 v143, v179, v35
	v_cvt_pk_bf16_f32 v187, v142, v143
	ds_write_b16 v202, v187 offset:1536
	ds_write_b16_d16_hi v210, v187 offset:1536
	v_mul_f32_e32 v176, v99, v143
	v_mul_f32_e32 v178, v98, v143
	v_fma_f32 v177, v98, v142, -v176
	v_fma_f32 v179, v99, v142, v178
	v_add_f32_e32 v142, v177, v16
	v_add_f32_e32 v143, v179, v48
	v_cvt_pk_bf16_f32 v184, v142, v143
	ds_write_b16 v203, v184 offset:2048
	ds_write_b16_d16_hi v211, v184 offset:2048
	v_mul_f32_e32 v176, v99, v143
	v_mul_f32_e32 v178, v98, v143
	v_fma_f32 v177, v98, v142, -v176
	v_fma_f32 v179, v99, v142, v178
	v_add_f32_e32 v142, v177, v17
	v_add_f32_e32 v143, v179, v49
	v_cvt_pk_bf16_f32 v185, v142, v143
	ds_write_b16 v204, v185 offset:2560
	ds_write_b16_d16_hi v212, v185 offset:2560
	v_mul_f32_e32 v176, v99, v143
	v_mul_f32_e32 v178, v98, v143
	v_fma_f32 v177, v98, v142, -v176
	v_fma_f32 v179, v99, v142, v178
	v_add_f32_e32 v142, v177, v18
	v_add_f32_e32 v143, v179, v50
	v_cvt_pk_bf16_f32 v186, v142, v143
	ds_write_b16 v205, v186 offset:3072
	ds_write_b16_d16_hi v213, v186 offset:3072
	v_mul_f32_e32 v176, v99, v143
	v_mul_f32_e32 v178, v98, v143
	v_fma_f32 v177, v98, v142, -v176
	v_fma_f32 v179, v99, v142, v178
	v_add_f32_e32 v142, v177, v19
; #define LAS __attribute__((address_space(3)))
; __device__ __forceinline__ unsigned f2bf(float f) { unsigned u = __builtin_bit_cast(unsigned, f); return (u + 0x7fffu + ((u >> 16) & 1u)) >> 16; }
; template <bool OUT>
; __device__ __forceinline__ void ssm_fast(KArgs ap, int l, LAS unsigned char* lds, const Ctx cx) {
;     ...
;             for (int t = 0; t < 32; ++t) {
;                 const float br = *(const LAS float*)(BU + (t * 128 + p) * 4), bi = *(const LAS float*)(BU + (t * 128 + 64 + p) * 4);
;                 const float nr = are * sr - aim * si + br, ni = are * si + aim * sr + bi; sr = nr; si = ni;
;                 if (OUT) { asm volatile("" ::: "memory");
;                     *(LAS bf16_t*)(BU + t * 512 + ((((p >> 3)) ^ (t & 15)) << 4) + (p & 7) * 2) = (bf16_t)f2bf(sr);
;                     *(LAS bf16_t*)(BU + t * 512 + (((8 + (p >> 3)) ^ (t & 15)) << 4) + (p & 7) * 2) = (bf16_t)f2bf(si); }
	v_add_f32_e32 v143, v179, v51
	v_cvt_pk_bf16_f32 v187, v142, v143
	ds_write_b16 v206, v187 offset:3584
	ds_write_b16_d16_hi v214, v187 offset:3584
	v_mul_f32_e32 v176, v99, v143
	v_mul_f32_e32 v178, v98, v143
	v_fma_f32 v177, v98, v142, -v176
	v_fma_f32 v179, v99, v142, v178
	v_add_f32_e32 v142, v177, v4
	v_add_f32_e32 v143, v179, v36
	v_cvt_pk_bf16_f32 v184, v142, v143
	ds_write_b16 v207, v184 offset:4096
	ds_write_b16_d16_hi v199, v184 offset:4096
	v_mul_f32_e32 v176, v99, v143
	v_mul_f32_e32 v178, v98, v143
	v_fma_f32 v177, v98, v142, -v176
	v_fma_f32 v179, v99, v142, v178
	v_add_f32_e32 v142, v177, v5
	v_add_f32_e32 v143, v179, v37
	v_cvt_pk_bf16_f32 v185, v142, v143
	ds_write_b16 v208, v185 offset:4608
	ds_write_b16_d16_hi v200, v185 offset:4608
	v_mul_f32_e32 v176, v99, v143
	v_mul_f32_e32 v178, v98, v143
	v_fma_f32 v177, v98, v142, -v176
	v_fma_f32 v179, v99, v142, v178
	v_add_f32_e32 v142, v177, v6
	v_add_f32_e32 v143, v179, v38
	v_cvt_pk_bf16_f32 v186, v142, v143
	ds_write_b16 v209, v186 offset:5120
	ds_write_b16_d16_hi v201, v186 offset:5120
	v_mul_f32_e32 v176, v99, v143
	v_mul_f32_e32 v178, v98, v143
	v_fma_f32 v177, v98, v142, -v176
	v_fma_f32 v179, v99, v142, v178
	v_add_f32_e32 v142, v177, v7
	v_add_f32_e32 v143, v179, v39
	v_cvt_pk_bf16_f32 v187, v142, v143
	ds_write_b16 v210, v187 offset:5632
	ds_write_b16_d16_hi v202, v187 offset:5632
	v_mul_f32_e32 v176, v99, v143
	v_mul_f32_e32 v178, v98, v143
	v_fma_f32 v177, v98, v142, -v176
	v_fma_f32 v179, v99, v142, v178
	v_add_f32_e32 v142, v177, v20
	v_add_f32_e32 v143, v179, v52
	v_cvt_pk_bf16_f32 v184, v142, v143
	ds_write_b16 v211, v184 offset:6144
	ds_write_b16_d16_hi v203, v184 offset:6144
	v_mul_f32_e32 v176, v99, v143
	v_mul_f32_e32 v178, v98, v143
	v_fma_f32 v177, v98, v142, -v176
	v_fma_f32 v179, v99, v142, v178
	v_add_f32_e32 v142, v177, v21
	v_add_f32_e32 v143, v179, v53
	v_cvt_pk_bf16_f32 v185, v142, v143
	ds_write_b16 v212, v185 offset:6656
	ds_write_b16_d16_hi v204, v185 offset:6656
	v_mul_f32_e32 v176, v99, v143
	v_mul_f32_e32 v178, v98, v143
	v_fma_f32 v177, v98, v142, -v176
	v_fma_f32 v179, v99, v142, v178
	v_add_f32_e32 v142, v177, v22
	v_add_f32_e32 v143, v179, v54
	v_cvt_pk_bf16_f32 v186, v142, v143
	ds_write_b16 v213, v186 offset:7168
	ds_write_b16_d16_hi v205, v186 offset:7168
	v_mul_f32_e32 v176, v99, v143
	v_mul_f32_e32 v178, v98, v143
	v_fma_f32 v177, v98, v142, -v176
	v_fma_f32 v179, v99, v142, v178
	v_add_f32_e32 v142, v177, v23
	v_add_f32_e32 v143, v179, v55
	v_cvt_pk_bf16_f32 v187, v142, v143
	ds_write_b16 v214, v187 offset:7680
	ds_write_b16_d16_hi v206, v187 offset:7680
	v_mul_f32_e32 v176, v99, v143
	v_mul_f32_e32 v178, v98, v143
	v_fma_f32 v177, v98, v142, -v176
	v_fma_f32 v179, v99, v142, v178
	v_add_f32_e32 v142, v177, v8
	v_add_f32_e32 v143, v179, v40
	v_cvt_pk_bf16_f32 v184, v142, v143
	ds_write_b16 v199, v184 offset:8192
	ds_write_b16_d16_hi v207, v184 offset:8192
	v_mul_f32_e32 v176, v99, v143
	v_mul_f32_e32 v178, v98, v143
	v_fma_f32 v177, v98, v142, -v176
	v_fma_f32 v179, v99, v142, v178
	v_add_f32_e32 v142, v177, v9
	v_add_f32_e32 v143, v179, v41
	v_cvt_pk_bf16_f32 v185, v142, v143
	ds_write_b16 v200, v185 offset:8704
	ds_write_b16_d16_hi v208, v185 offset:8704
	v_mul_f32_e32 v176, v99, v143
	v_mul_f32_e32 v178, v98, v143
	v_fma_f32 v177, v98, v142, -v176
	v_fma_f32 v179, v99, v142, v178
	v_add_f32_e32 v142, v177, v10
	v_add_f32_e32 v143, v179, v42
	v_cvt_pk_bf16_f32 v186, v142, v143
	ds_write_b16 v201, v186 offset:9216
	ds_write_b16_d16_hi v209, v186 offset:9216
	v_mul_f32_e32 v176, v99, v143
	v_mul_f32_e32 v178, v98, v143
	v_fma_f32 v177, v98, v142, -v176
	v_fma_f32 v179, v99, v142, v178
	v_add_f32_e32 v142, v177, v11
	v_add_f32_e32 v143, v179, v43
	v_cvt_pk_bf16_f32 v187, v142, v143
	ds_write_b16 v202, v187 offset:9728
	ds_write_b16_d16_hi v210, v187 offset:9728
	v_mul_f32_e32 v176, v99, v143
	v_mul_f32_e32 v178, v98, v143
	v_fma_f32 v177, v98, v142, -v176
	v_fma_f32 v179, v99, v142, v178
	v_add_f32_e32 v142, v177, v24
	v_add_f32_e32 v143, v179, v56
	v_cvt_pk_bf16_f32 v184, v142, v143
	ds_write_b16 v203, v184 offset:10240
	ds_write_b16_d16_hi v211, v184 offset:10240
	v_mul_f32_e32 v176, v99, v143
	v_mul_f32_e32 v178, v98, v143
	v_fma_f32 v177, v98, v142, -v176
	v_fma_f32 v179, v99, v142, v178
	v_add_f32_e32 v142, v177, v25
	v_add_f32_e32 v143, v179, v57
	v_cvt_pk_bf16_f32 v185, v142, v143
	ds_write_b16 v204, v185 offset:10752
	ds_write_b16_d16_hi v212, v185 offset:10752
	v_mul_f32_e32 v176, v99, v143
	v_mul_f32_e32 v178, v98, v143
	v_fma_f32 v177, v98, v142, -v176
	v_fma_f32 v179, v99, v142, v178
	v_add_f32_e32 v142, v177, v26
	v_add_f32_e32 v143, v179, v58
	v_cvt_pk_bf16_f32 v186, v142, v143
	ds_write_b16 v205, v186 offset:11264
	ds_write_b16_d16_hi v213, v186 offset:11264
	v_mul_f32_e32 v176, v99, v143
	v_mul_f32_e32 v178, v98, v143
	v_fma_f32 v177, v98, v142, -v176
	v_fma_f32 v179, v99, v142, v178
	v_add_f32_e32 v142, v177, v27
	v_add_f32_e32 v143, v179, v59
	v_cvt_pk_bf16_f32 v187, v142, v143
	ds_write_b16 v206, v187 offset:11776
	ds_write_b16_d16_hi v214, v187 offset:11776
	v_mul_f32_e32 v176, v99, v143
	v_mul_f32_e32 v178, v98, v143
	v_fma_f32 v177, v98, v142, -v176
	v_fma_f32 v179, v99, v142, v178
	v_add_f32_e32 v142, v177, v12
	v_add_f32_e32 v143, v179, v44
	v_cvt_pk_bf16_f32 v184, v142, v143
	ds_write_b16 v207, v184 offset:12288
	ds_write_b16_d16_hi v199, v184 offset:12288
	v_mul_f32_e32 v176, v99, v143
	v_mul_f32_e32 v178, v98, v143
	v_fma_f32 v177, v98, v142, -v176
	v_fma_f32 v179, v99, v142, v178
	v_add_f32_e32 v142, v177, v13
	v_add_f32_e32 v143, v179, v45
	v_cvt_pk_bf16_f32 v185, v142, v143
	ds_write_b16 v208, v185 offset:12800
; #define LAS __attribute__((address_space(3)))
; __device__ __forceinline__ unsigned f2bf(float f) { unsigned u = __builtin_bit_cast(unsigned, f); return (u + 0x7fffu + ((u >> 16) & 1u)) >> 16; }
; #define MFMA16(a_, b_, c_) __builtin_amdgcn_mfma_f32_16x16x32_bf16((a_), (b_), (c_), 0, 0, 0)
; #define WAVE_FENCE() asm volatile("s_waitcnt lgkmcnt(0)" ::: "memory")
; template <bool OUT>
; __device__ __forceinline__ void ssm_fast(KArgs ap, int l, LAS unsigned char* lds, const Ctx cx) {
;     ...
;             for (int t = 0; t < 32; ++t) {
;                 const float br = *(const LAS float*)(BU + (t * 128 + p) * 4), bi = *(const LAS float*)(BU + (t * 128 + 64 + p) * 4);
;                 const float nr = are * sr - aim * si + br, ni = are * si + aim * sr + bi; sr = nr; si = ni;
;                 if (OUT) { asm volatile("" ::: "memory");
;                     *(LAS bf16_t*)(BU + t * 512 + ((((p >> 3)) ^ (t & 15)) << 4) + (p & 7) * 2) = (bf16_t)f2bf(sr);
;                     *(LAS bf16_t*)(BU + t * 512 + (((8 + (p >> 3)) ^ (t & 15)) << 4) + (p & 7) * 2) = (bf16_t)f2bf(si); }
;             }
;             if (OUT) {
;                 WAVE_FENCE();
;                 const int row = lane & 15, kq = lane >> 4;
; #pragma unroll
;                 for (int tbk = 0; tbk < 2; ++tbk) { f32x4 acc = (f32x4){0.f, 0.f, 0.f, 0.f};
; #pragma unroll
;                     for (int ks = 0; ks < 4; ++ks) { const bf16x8 af = *(const LAS bf16x8*)(BU + (tbk * 16 + row) * 512 + (((ks * 4 + kq) ^ row) << 4)); acc = MFMA16(af, ct[ks], acc); }
; #pragma unroll
;                     for (int j = 0; j < 4; ++j) { const size_t tok = tk + tbk * 16 + 4 * kq + j;
;                         const float uval = bf2f(uv[tbk][j]);
;                         ypre[tok * 512 + g * 16 + row] = (bf16_t)f2bf(gelu_tanh(acc[j] + dsk * uval)); } }
	ds_write_b16_d16_hi v200, v185 offset:12800
	v_mul_f32_e32 v176, v99, v143
	v_mul_f32_e32 v178, v98, v143
	v_fma_f32 v177, v98, v142, -v176
	v_fma_f32 v179, v99, v142, v178
	v_add_f32_e32 v142, v177, v14
	v_add_f32_e32 v143, v179, v46
	v_cvt_pk_bf16_f32 v186, v142, v143
	ds_write_b16 v209, v186 offset:13312
	ds_write_b16_d16_hi v201, v186 offset:13312
	v_mul_f32_e32 v176, v99, v143
	v_mul_f32_e32 v178, v98, v143
	v_fma_f32 v177, v98, v142, -v176
	v_fma_f32 v179, v99, v142, v178
	v_add_f32_e32 v142, v177, v15
	v_add_f32_e32 v143, v179, v47
	v_cvt_pk_bf16_f32 v187, v142, v143
	ds_write_b16 v210, v187 offset:13824
	ds_write_b16_d16_hi v202, v187 offset:13824
	v_mul_f32_e32 v176, v99, v143
	v_mul_f32_e32 v178, v98, v143
	v_fma_f32 v177, v98, v142, -v176
	v_fma_f32 v179, v99, v142, v178
	v_add_f32_e32 v142, v177, v28
	v_add_f32_e32 v143, v179, v60
	v_cvt_pk_bf16_f32 v184, v142, v143
	ds_write_b16 v211, v184 offset:14336
	ds_write_b16_d16_hi v203, v184 offset:14336
	v_mul_f32_e32 v176, v99, v143
	v_mul_f32_e32 v178, v98, v143
	v_fma_f32 v177, v98, v142, -v176
	v_fma_f32 v179, v99, v142, v178
	v_add_f32_e32 v142, v177, v29
	v_add_f32_e32 v143, v179, v61
	v_cvt_pk_bf16_f32 v185, v142, v143
	ds_write_b16 v212, v185 offset:14848
	ds_write_b16_d16_hi v204, v185 offset:14848
	v_mul_f32_e32 v176, v99, v143
	v_mul_f32_e32 v178, v98, v143
	v_fma_f32 v177, v98, v142, -v176
	v_fma_f32 v179, v99, v142, v178
	v_add_f32_e32 v142, v177, v30
	v_add_f32_e32 v143, v179, v62
	v_cvt_pk_bf16_f32 v186, v142, v143
	ds_write_b16 v213, v186 offset:15360
	ds_write_b16_d16_hi v205, v186 offset:15360
	v_mul_f32_e32 v176, v99, v143
	v_mul_f32_e32 v178, v98, v143
	v_fma_f32 v177, v98, v142, -v176
	v_fma_f32 v179, v99, v142, v178
	v_add_f32_e32 v142, v177, v31
	v_add_f32_e32 v143, v179, v63
	v_cvt_pk_bf16_f32 v187, v142, v143
	ds_write_b16 v214, v187 offset:15872
	ds_write_b16_d16_hi v206, v187 offset:15872
	s_waitcnt lgkmcnt(0)
	ds_read_b128 v[0:3], v111
	ds_read_b128 v[8:11], v113
	ds_read_b128 v[4:7], v115
	ds_read_b128 v[14:17], v111 offset:8192
	ds_read_b128 v[18:21], v117
	ds_read_b128 v[22:25], v113 offset:8192
	s_waitcnt vmcnt(7)
	v_lshlrev_b32_e32 v28, 16, v144
	v_mov_b32_e32 v13, s9
	v_or_b32_e32 v12, s8, v102
	v_lshlrev_b64 v[12:13], 10, v[12:13]
	v_lshl_add_u64 v[12:13], v[134:135], 0, v[12:13]
	s_waitcnt lgkmcnt(5)
	v_mfma_f32_16x16x32_bf16 v[0:3], v[0:3], v[76:79], 0
	s_waitcnt vmcnt(6)
	v_lshlrev_b32_e32 v29, 16, v131
	v_mov_b32_e32 v27, s9
	v_or_b32_e32 v26, s8, v120
	s_waitcnt lgkmcnt(4)
	v_mfma_f32_16x16x32_bf16 v[0:3], v[8:11], v[84:87], v[0:3]
	ds_read_b128 v[8:11], v115 offset:8192
	s_add_i32 s1, s1, 1
	s_cmp_eq_u32 s1, 4
	s_waitcnt lgkmcnt(4)
	v_mfma_f32_16x16x32_bf16 v[0:3], v[4:7], v[88:91], v[0:3]
	ds_read_b128 v[4:7], v117 offset:8192
	s_waitcnt lgkmcnt(3)
	v_mfma_f32_16x16x32_bf16 v[0:3], v[18:21], v[92:95], v[0:3]
	s_nop 7
	v_fma_f32 v0, v97, v28, v0
	v_mul_f32_e32 v18, 0x3d372713, v0
	v_mul_f32_e32 v18, v0, v18
	v_fma_f32 v18, v0, v18, v0
	v_mul_f32_e32 v18, 0x3f4c422a, v18
	v_add_f32_e32 v18, v18, v18
	v_mul_f32_e32 v18, 0x3fb8aa3b, v18
	v_exp_f32_e32 v18, v18
	v_mul_f32_e32 v0, 0.5, v0
	v_fma_f32 v1, v97, v29, v1
	v_mul_f32_e32 v19, 0x3d372713, v1
	v_add_f32_e32 v18, 1.0, v18
	v_rcp_f32_e32 v18, v18
	v_mul_f32_e32 v19, v1, v19
	v_fma_f32 v19, v1, v19, v1
	v_mul_f32_e32 v19, 0x3f4c422a, v19
	v_fma_f32 v18, v18, -2.0, 1.0
	v_add_f32_e32 v18, 1.0, v18
	v_mul_f32_e32 v0, v0, v18
	v_bfe_u32 v18, v0, 16, 1
	v_add3_u32 v0, v0, v18, s45
	global_store_short_d16_hi v[12:13], v0, off
	s_waitcnt vmcnt(6)
	v_lshlrev_b32_e32 v12, 16, v129
	v_fma_f32 v2, v97, v12, v2
	v_mul_f32_e32 v12, 0x3d372713, v2
	v_mul_f32_e32 v12, v2, v12
	v_fma_f32 v12, v2, v12, v2
	v_mul_f32_e32 v12, 0x3f4c422a, v12
	v_add_f32_e32 v12, v12, v12
	v_mul_f32_e32 v12, 0x3fb8aa3b, v12
	v_exp_f32_e32 v12, v12
	v_add_f32_e32 v19, v19, v19
	v_mul_f32_e32 v19, 0x3fb8aa3b, v19
	v_exp_f32_e32 v19, v19
	v_add_f32_e32 v12, 1.0, v12
	v_rcp_f32_e32 v12, v12
	v_mul_f32_e32 v2, 0.5, v2
	v_add_f32_e32 v19, 1.0, v19
	v_rcp_f32_e32 v19, v19
	v_fma_f32 v12, v12, -2.0, 1.0
	v_add_f32_e32 v12, 1.0, v12
	v_mul_f32_e32 v2, v2, v12
	v_bfe_u32 v12, v2, 16, 1
	v_add3_u32 v2, v2, v12, s45
	s_waitcnt vmcnt(5)
; #define LAS __attribute__((address_space(3)))
; __device__ __forceinline__ unsigned f2bf(float f) { unsigned u = __builtin_bit_cast(unsigned, f); return (u + 0x7fffu + ((u >> 16) & 1u)) >> 16; }
; #define MFMA16(a_, b_, c_) __builtin_amdgcn_mfma_f32_16x16x32_bf16((a_), (b_), (c_), 0, 0, 0)
; #define WAVE_FENCE() asm volatile("s_waitcnt lgkmcnt(0)" ::: "memory")
; template <bool OUT>
; __device__ __forceinline__ void ssm_fast(KArgs ap, int l, LAS unsigned char* lds, const Ctx cx) {
;     ...
;             if (OUT) {
;                 WAVE_FENCE();
;                 const int row = lane & 15, kq = lane >> 4;
; #pragma unroll
;                 for (int tbk = 0; tbk < 2; ++tbk) { f32x4 acc = (f32x4){0.f, 0.f, 0.f, 0.f};
; #pragma unroll
;                     for (int ks = 0; ks < 4; ++ks) { const bf16x8 af = *(const LAS bf16x8*)(BU + (tbk * 16 + row) * 512 + (((ks * 4 + kq) ^ row) << 4)); acc = MFMA16(af, ct[ks], acc); }
; #pragma unroll
;                     for (int j = 0; j < 4; ++j) { const size_t tok = tk + tbk * 16 + 4 * kq + j;
;                         const float uval = bf2f(uv[tbk][j]);
;                         ypre[tok * 512 + g * 16 + row] = (bf16_t)f2bf(gelu_tanh(acc[j] + dsk * uval)); } }
;             }
;         }
	v_lshlrev_b32_e32 v12, 16, v127
	v_fmac_f32_e32 v3, v97, v12
	v_mul_f32_e32 v12, 0x3d372713, v3
	v_fma_f32 v0, v19, -2.0, 1.0
	v_mul_f32_e32 v12, v3, v12
	v_mul_f32_e32 v1, 0.5, v1
	v_add_f32_e32 v0, 1.0, v0
	v_fma_f32 v12, v3, v12, v3
	v_mul_f32_e32 v0, v1, v0
	v_mul_f32_e32 v12, 0x3f4c422a, v12
	v_bfe_u32 v1, v0, 16, 1
	v_add_f32_e32 v12, v12, v12
	v_add3_u32 v13, v0, v1, s45
	v_lshlrev_b64 v[0:1], 10, v[26:27]
	v_mul_f32_e32 v12, 0x3fb8aa3b, v12
	v_lshl_add_u64 v[0:1], v[134:135], 0, v[0:1]
	v_exp_f32_e32 v18, v12
	global_store_short_d16_hi v[0:1], v13, off
	v_mov_b32_e32 v1, s9
	v_or_b32_e32 v0, s8, v122
	v_mfma_f32_16x16x32_bf16 v[12:15], v[14:17], v[76:79], 0
	v_lshlrev_b64 v[0:1], 10, v[0:1]
	v_lshl_add_u64 v[0:1], v[134:135], 0, v[0:1]
	global_store_short_d16_hi v[0:1], v2, off
	v_add_f32_e32 v0, 1.0, v18
	v_rcp_f32_e32 v0, v0
	s_waitcnt lgkmcnt(2)
	v_mfma_f32_16x16x32_bf16 v[12:15], v[22:25], v[84:87], v[12:15]
	v_mul_f32_e32 v19, 0.5, v3
	v_mov_b32_e32 v17, s9
	v_fma_f32 v18, v0, -2.0, 1.0
	s_waitcnt lgkmcnt(1)
	v_mfma_f32_16x16x32_bf16 v[0:3], v[8:11], v[88:91], v[12:15]
	v_add_f32_e32 v8, 1.0, v18
	v_or_b32_e32 v16, s8, v124
	v_mul_f32_e32 v8, v19, v8
	s_waitcnt lgkmcnt(0)
	v_mfma_f32_16x16x32_bf16 v[0:3], v[4:7], v[92:95], v[0:3]
	s_waitcnt vmcnt(6)
	v_lshlrev_b32_e32 v4, 16, v125
	v_bfe_u32 v9, v8, 16, 1
	v_add3_u32 v7, v8, v9, s45
	s_nop 3
	v_fma_f32 v0, v97, v4, v0
	v_mul_f32_e32 v4, 0x3d372713, v0
	v_mul_f32_e32 v4, v0, v4
	v_fma_f32 v4, v0, v4, v0
	v_mul_f32_e32 v4, 0x3f4c422a, v4
	v_add_f32_e32 v4, v4, v4
	v_mul_f32_e32 v4, 0x3fb8aa3b, v4
	v_exp_f32_e32 v6, v4
	v_lshlrev_b64 v[4:5], 10, v[16:17]
	v_lshl_add_u64 v[4:5], v[134:135], 0, v[4:5]
	global_store_short_d16_hi v[4:5], v7, off
	v_add_f32_e32 v6, 1.0, v6
	v_rcp_f32_e32 v6, v6
	s_waitcnt vmcnt(6)
	v_lshlrev_b32_e32 v7, 16, v123
	v_fma_f32 v7, v97, v7, v1
	v_mul_f32_e32 v1, 0x3d372713, v7
	v_mul_f32_e32 v1, v7, v1
	v_fma_f32 v6, v6, -2.0, 1.0
	v_fma_f32 v1, v7, v1, v7
	v_mul_f32_e32 v0, 0.5, v0
	v_add_f32_e32 v6, 1.0, v6
	v_mul_f32_e32 v1, 0x3f4c422a, v1
	v_mul_f32_e32 v0, v0, v6
	v_add_f32_e32 v1, v1, v1
	v_mov_b32_e32 v5, s9
	v_or_b32_e32 v4, s8, v104
	v_bfe_u32 v6, v0, 16, 1
	v_mul_f32_e32 v1, 0x3fb8aa3b, v1
	v_exp_f32_e32 v8, v1
	v_add3_u32 v6, v0, v6, s45
	v_lshlrev_b64 v[0:1], 10, v[4:5]
	v_lshl_add_u64 v[0:1], v[134:135], 0, v[0:1]
	global_store_short_d16_hi v[0:1], v6, off
	s_waitcnt vmcnt(6)
	v_lshlrev_b32_e32 v6, 16, v121
	v_fma_f32 v2, v97, v6, v2
	v_mul_f32_e32 v6, 0x3d372713, v2
	v_add_f32_e32 v4, 1.0, v8
	v_mul_f32_e32 v6, v2, v6
	v_rcp_f32_e32 v4, v4
	v_fma_f32 v6, v2, v6, v2
	v_mul_f32_e32 v6, 0x3f4c422a, v6
	v_add_f32_e32 v6, v6, v6
	v_mul_f32_e32 v6, 0x3fb8aa3b, v6
	v_fma_f32 v4, v4, -2.0, 1.0
	v_exp_f32_e32 v6, v6
	v_mul_f32_e32 v5, 0.5, v7
	v_add_f32_e32 v4, 1.0, v4
	v_mul_f32_e32 v4, v5, v4
	v_bfe_u32 v5, v4, 16, 1
	v_add3_u32 v4, v4, v5, s45
	v_add_f32_e32 v5, 1.0, v6
	v_rcp_f32_e32 v5, v5
	v_mov_b32_e32 v1, s9
	v_or_b32_e32 v0, s8, v126
	v_lshlrev_b64 v[0:1], 10, v[0:1]
	v_lshl_add_u64 v[0:1], v[134:135], 0, v[0:1]
	global_store_short_d16_hi v[0:1], v4, off
	v_fma_f32 v4, v5, -2.0, 1.0
	s_waitcnt vmcnt(6)
	v_lshlrev_b32_e32 v5, 16, v119
	v_fmac_f32_e32 v3, v97, v5
	v_mul_f32_e32 v5, 0x3d372713, v3
	v_mul_f32_e32 v5, v3, v5
	v_fma_f32 v5, v3, v5, v3
	v_mul_f32_e32 v5, 0x3f4c422a, v5
	v_add_f32_e32 v5, v5, v5
	v_mul_f32_e32 v5, 0x3fb8aa3b, v5
	v_exp_f32_e32 v5, v5
	v_mul_f32_e32 v2, 0.5, v2
	v_add_f32_e32 v4, 1.0, v4
	v_mul_f32_e32 v2, v2, v4
	v_bfe_u32 v4, v2, 16, 1
	v_add3_u32 v2, v2, v4, s45
	v_add_f32_e32 v4, 1.0, v5
	v_rcp_f32_e32 v4, v4
	v_mov_b32_e32 v1, s9
	v_or_b32_e32 v0, s8, v128
	v_lshlrev_b64 v[0:1], 10, v[0:1]
	v_lshl_add_u64 v[0:1], v[134:135], 0, v[0:1]
	global_store_short_d16_hi v[0:1], v2, off
	v_fma_f32 v2, v4, -2.0, 1.0
	v_mul_f32_e32 v3, 0.5, v3
	v_add_f32_e32 v2, 1.0, v2
	v_mov_b32_e32 v1, s9
	v_or_b32_e32 v0, s8, v130
	v_mul_f32_e32 v2, v3, v2
	v_bfe_u32 v3, v2, 16, 1
	v_lshlrev_b64 v[0:1], 10, v[0:1]
	v_add3_u32 v2, v2, v3, s45
	v_lshl_add_u64 v[0:1], v[134:135], 0, v[0:1]
	global_store_short_d16_hi v[0:1], v2, off
	s_cbranch_scc0 .LBB0_311
	s_add_i32 s0, s0, s7
	s_cmpk_gt_i32 s0, 0x1fff
	s_cbranch_scc0 .LBB0_310

; __device__ __forceinline__ unsigned pk2(float lo, float hi) { return f2bf(lo) | (f2bf(hi) << 16); }
; __device__ __forceinline__ void phase_branch_norm(bf16_t* y, const float* ga, const float* gs, const float* gg, const Ctx cx) {
;     ...
;     for (int m = gw; m < T; m += NGW) {
;         bf16_t* yr = y + (size_t)m * DM + lane * 8;
;         float v[4][8]; float ss[4];
; #pragma unroll
;         for (int j = 0; j < 4; ++j) { const u32x4 w = *(const u32x4*)(yr + j * 512);
;             v[j][0] = bflo(w.x); v[j][1] = bfhi(w.x); v[j][2] = bflo(w.y); v[j][3] = bfhi(w.y); v[j][4] = bflo(w.z); v[j][5] = bfhi(w.z); v[j][6] = bflo(w.w); v[j][7] = bfhi(w.w);
;             float s = 0.f;
; #pragma unroll
;             for (int e = 0; e < 8; ++e) s += v[j][e] * v[j][e];
;             ss[j] = s; }
;         const float sa = wave_sum(ss[0] + ss[1]), s2 = wave_sum(ss[2]), s3 = wave_sum(ss[3]);
;         const float ra = 1.0f / sqrtf(sa * (1.0f / 1024.f) + EPS), rs = 1.0f / sqrtf(s2 * (1.0f / 512.f) + EPS), rg = 1.0f / sqrtf(s3 * (1.0f / 512.f) + EPS);
; #pragma unroll
;         for (int j = 0; j < 4; ++j) { const float r = (j < 2) ? ra : (j == 2 ? rs : rg);
;             u32x4 w; w.x = pk2(v[j][0] * r * gv[j][0], v[j][1] * r * gv[j][1]); w.y = pk2(v[j][2] * r * gv[j][2], v[j][3] * r * gv[j][3]);
;             w.z = pk2(v[j][4] * r * gv[j][4], v[j][5] * r * gv[j][5]); w.w = pk2(v[j][6] * r * gv[j][6], v[j][7] * r * gv[j][7]);
;             *(u32x4*)(yr + j * 512) = w; }
.LBB0_467:
	global_load_dwordx4 v[46:49], v[38:39], off
	global_load_dwordx4 v[54:57], v[38:39], off offset:1024
	global_load_dwordx4 v[34:37], v[38:39], off offset:2048
	global_load_dwordx4 v[30:33], v[38:39], off offset:3072
	s_add_i32 s4, s4, s6
	s_cmp_lt_i32 s4, 0x8000
	s_waitcnt vmcnt(3)
	v_and_b32_e32 v44, 0xffff0000, v46
	s_waitcnt vmcnt(2)
	v_and_b32_e32 v52, 0xffff0000, v54
	v_lshlrev_b32_e32 v42, 16, v46
	v_lshlrev_b32_e32 v50, 16, v54
	v_mov_b32_e32 v68, v44
	v_mov_b32_e32 v69, v52
	v_lshlrev_b32_e32 v43, 16, v47
	v_lshlrev_b32_e32 v51, 16, v55
	v_mov_b32_e32 v60, v42
	v_mov_b32_e32 v61, v50
	v_pk_mul_f32 v[68:69], v[68:69], v[68:69]
	v_and_b32_e32 v45, 0xffff0000, v47
	v_and_b32_e32 v53, 0xffff0000, v55
	v_mov_b32_e32 v70, v43
	v_mov_b32_e32 v71, v51
	v_pk_fma_f32 v[60:61], v[60:61], v[60:61], v[68:69]
	v_lshlrev_b32_e32 v46, 16, v48
	v_lshlrev_b32_e32 v54, 16, v56
	v_mov_b32_e32 v72, v45
	v_mov_b32_e32 v73, v53
	v_pk_fma_f32 v[60:61], v[70:71], v[70:71], v[60:61]
	v_and_b32_e32 v48, 0xffff0000, v48
	v_and_b32_e32 v56, 0xffff0000, v56
	v_mov_b32_e32 v74, v46
	v_mov_b32_e32 v75, v54
	v_pk_fma_f32 v[60:61], v[72:73], v[72:73], v[60:61]
	v_lshlrev_b32_e32 v47, 16, v49
	v_lshlrev_b32_e32 v55, 16, v57
	v_mov_b32_e32 v76, v48
	v_mov_b32_e32 v77, v56
	v_pk_fma_f32 v[60:61], v[74:75], v[74:75], v[60:61]
	v_and_b32_e32 v49, 0xffff0000, v49
	v_and_b32_e32 v57, 0xffff0000, v57
	v_mov_b32_e32 v78, v47
	v_mov_b32_e32 v79, v55
	v_pk_fma_f32 v[60:61], v[76:77], v[76:77], v[60:61]
	v_mov_b32_e32 v80, v49
	v_mov_b32_e32 v81, v57
	v_pk_fma_f32 v[60:61], v[78:79], v[78:79], v[60:61]
	s_waitcnt vmcnt(1)
	v_lshlrev_b32_e32 v59, 16, v35
	v_pk_fma_f32 v[60:61], v[80:81], v[80:81], v[60:61]
	v_lshlrev_b32_e32 v58, 16, v34
	v_add_f32_e32 v68, v60, v61
	ds_bpermute_b32 v69, v62, v68
	v_and_b32_e32 v61, 0xffff0000, v35
	v_and_b32_e32 v60, 0xffff0000, v34
	v_lshlrev_b32_e32 v35, 16, v37
	v_lshlrev_b32_e32 v34, 16, v36
	s_waitcnt lgkmcnt(0)
	v_add_f32_e32 v70, v68, v69
	ds_bpermute_b32 v71, v63, v70
	v_pk_mul_f32 v[68:69], v[58:59], v[58:59]
	v_and_b32_e32 v37, 0xffff0000, v37
	v_and_b32_e32 v36, 0xffff0000, v36
	v_mov_b32_e32 v72, v37
	s_waitcnt lgkmcnt(0)
	v_add_f32_e32 v74, v70, v71
	ds_bpermute_b32 v75, v64, v74
	v_pk_mul_f32 v[70:71], v[60:61], v[60:61]
	v_mov_b32_e32 v73, v35
	v_add_f32_e32 v68, v68, v70
	v_add_f32_e32 v68, v69, v68
	s_waitcnt lgkmcnt(0)
	v_add_f32_e32 v74, v74, v75
	ds_bpermute_b32 v75, v65, v74
	v_add_f32_e32 v68, v71, v68
	v_fmac_f32_e32 v68, v34, v34
	v_pk_mul_f32 v[72:73], v[72:73], v[72:73]
	v_fmac_f32_e32 v68, v36, v36
	s_waitcnt lgkmcnt(0)
	v_add_f32_e32 v69, v74, v75
	ds_bpermute_b32 v70, v66, v69
	v_add_f32_e32 v68, v73, v68
	v_add_f32_e32 v68, v72, v68
	ds_bpermute_b32 v71, v62, v68
	s_waitcnt lgkmcnt(1)
	v_add_f32_e32 v69, v69, v70
	ds_bpermute_b32 v70, v67, v69
	s_waitcnt lgkmcnt(1)
	v_add_f32_e32 v68, v68, v71
	ds_bpermute_b32 v71, v63, v68
	s_waitcnt lgkmcnt(1)
	v_add_f32_e32 v69, v69, v70
	v_fmamk_f32 v69, v69, 0x3a800000, v194
	v_mul_f32_e32 v70, 0x4f800000, v69
	v_cmp_gt_f32_e32 vcc, s13, v69
	s_waitcnt lgkmcnt(0)
	v_add_f32_e32 v71, v68, v71
	v_cndmask_b32_e32 v69, v69, v70, vcc
	v_sqrt_f32_e32 v70, v69
	s_nop 0
	v_add_u32_e32 v68, -1, v70
	v_add_u32_e32 v72, 1, v70
	v_fma_f32 v73, -v68, v70, v69
	v_fma_f32 v74, -v72, v70, v69
	v_cmp_ge_f32_e64 s[0:1], 0, v73
	s_nop 1
	v_cndmask_b32_e64 v68, v70, v68, s[0:1]
	v_cmp_lt_f32_e64 s[0:1], 0, v74
	s_nop 1
	v_cndmask_b32_e64 v68, v68, v72, s[0:1]
	v_mul_f32_e32 v70, 0x37800000, v68
	v_cndmask_b32_e32 v68, v68, v70, vcc
	v_cmp_class_f32_e32 vcc, v69, v195
	ds_bpermute_b32 v72, v64, v71
	s_nop 0
	v_cndmask_b32_e32 v68, v68, v69, vcc
	v_div_scale_f32 v69, s[0:1], v68, v68, 1.0
	v_rcp_f32_e32 v70, v69
	v_div_scale_f32 v73, vcc, 1.0, v68, 1.0
	v_fma_f32 v74, -v69, v70, 1.0
	v_fmac_f32_e32 v70, v74, v70
	v_mul_f32_e32 v74, v73, v70
	v_fma_f32 v75, -v69, v74, v73
	v_fmac_f32_e32 v74, v75, v70
	v_fma_f32 v69, -v69, v74, v73
	v_div_fmas_f32 v69, v69, v70, v74
	v_div_fixup_f32 v68, v69, v68, 1.0
	v_pk_mul_f32 v[42:43], v[68:69], v[42:43] op_sel_hi:[0,1]
	v_pk_mul_f32 v[46:47], v[68:69], v[46:47] op_sel_hi:[0,1]
	v_pk_mul_f32 v[48:49], v[68:69], v[48:49] op_sel_hi:[0,1]
	v_pk_mul_f32 v[44:45], v[68:69], v[44:45] op_sel_hi:[0,1]
	v_pk_mul_f32 v[50:51], v[68:69], v[50:51] op_sel_hi:[0,1]
	v_pk_mul_f32 v[52:53], v[68:69], v[52:53] op_sel_hi:[0,1]
	v_pk_mul_f32 v[54:55], v[68:69], v[54:55] op_sel_hi:[0,1]
	v_pk_mul_f32 v[56:57], v[68:69], v[56:57] op_sel_hi:[0,1]
	v_pk_mul_f32 v[68:69], v[16:17], v[42:43]
	v_pk_mul_f32 v[46:47], v[20:21], v[46:47]
	v_pk_mul_f32 v[48:49], v[18:19], v[48:49]
	v_pk_mul_f32 v[44:45], v[14:15], v[44:45]
	v_pk_mul_f32 v[42:43], v[24:25], v[50:51]
	v_pk_mul_f32 v[50:51], v[22:23], v[52:53]
	v_pk_mul_f32 v[52:53], v[28:29], v[54:55]
	v_pk_mul_f32 v[54:55], v[26:27], v[56:57]
	v_bfe_u32 v56, v49, 16, 1
	v_bfe_u32 v57, v48, 16, 1
	v_bfe_u32 v74, v68, 16, 1
	v_bfe_u32 v75, v69, 16, 1
	v_bfe_u32 v76, v46, 16, 1
	v_bfe_u32 v77, v47, 16, 1
	v_bfe_u32 v70, v45, 16, 1
	v_bfe_u32 v73, v44, 16, 1
	v_add3_u32 v48, v48, v57, s45
	v_add3_u32 v49, v49, v56, s45
	v_add3_u32 v47, v47, v77, s45
	v_add3_u32 v46, v46, v76, s45
	v_add3_u32 v56, v69, v75, s45
	v_add3_u32 v57, v68, v74, s45
	v_add3_u32 v44, v44, v73, s45
	v_add3_u32 v45, v45, v70, s45
	v_lshrrev_b32_e32 v57, 16, v57
	v_lshrrev_b32_e32 v56, 16, v56
	v_lshrrev_b32_e32 v46, 16, v46
	v_lshrrev_b32_e32 v47, 16, v47
	v_and_or_b32 v47, v49, s43, v47
	v_and_or_b32 v46, v48, s43, v46
	v_and_or_b32 v45, v45, s43, v56
	v_and_or_b32 v44, v44, s43, v57
	global_store_dwordx4 v[38:39], v[44:47], off
	v_bfe_u32 v48, v43, 16, 1
	v_bfe_u32 v49, v52, 16, 1
	s_waitcnt lgkmcnt(0)
; __device__ __forceinline__ unsigned pk2(float lo, float hi) { return f2bf(lo) | (f2bf(hi) << 16); }
; __device__ __forceinline__ void phase_branch_norm(bf16_t* y, const float* ga, const float* gs, const float* gg, const Ctx cx) {
;     ...
;         for (int j = 0; j < 4; ++j) { const u32x4 w = *(const u32x4*)(yr + j * 512);
;             v[j][0] = bflo(w.x); v[j][1] = bfhi(w.x); v[j][2] = bflo(w.y); v[j][3] = bfhi(w.y); v[j][4] = bflo(w.z); v[j][5] = bfhi(w.z); v[j][6] = bflo(w.w); v[j][7] = bfhi(w.w);
;             float s = 0.f;
; #pragma unroll
;             for (int e = 0; e < 8; ++e) s += v[j][e] * v[j][e];
;             ss[j] = s; }
;         const float sa = wave_sum(ss[0] + ss[1]), s2 = wave_sum(ss[2]), s3 = wave_sum(ss[3]);
;         const float ra = 1.0f / sqrtf(sa * (1.0f / 1024.f) + EPS), rs = 1.0f / sqrtf(s2 * (1.0f / 512.f) + EPS), rg = 1.0f / sqrtf(s3 * (1.0f / 512.f) + EPS);
; #pragma unroll
;         for (int j = 0; j < 4; ++j) { const float r = (j < 2) ? ra : (j == 2 ? rs : rg);
;             u32x4 w; w.x = pk2(v[j][0] * r * gv[j][0], v[j][1] * r * gv[j][1]); w.y = pk2(v[j][2] * r * gv[j][2], v[j][3] * r * gv[j][3]);
;             w.z = pk2(v[j][4] * r * gv[j][4], v[j][5] * r * gv[j][5]); w.w = pk2(v[j][6] * r * gv[j][6], v[j][7] * r * gv[j][7]);
;             *(u32x4*)(yr + j * 512) = w; }
	v_add_f32_e32 v44, v71, v72
	ds_bpermute_b32 v45, v65, v44
	v_bfe_u32 v47, v42, 16, 1
	v_add3_u32 v49, v52, v49, s45
	v_add3_u32 v43, v43, v48, s45
	v_bfe_u32 v78, v55, 16, 1
	s_waitcnt lgkmcnt(0)
	v_add_f32_e32 v44, v44, v45
	ds_bpermute_b32 v45, v66, v44
	v_add3_u32 v42, v42, v47, s45
	v_lshrrev_b32_e32 v47, 16, v49
	v_add3_u32 v46, v55, v78, s45
	v_bfe_u32 v55, v53, 16, 1
	s_waitcnt lgkmcnt(0)
	v_add_f32_e32 v44, v44, v45
	ds_bpermute_b32 v45, v67, v44
	v_add3_u32 v53, v53, v55, s45
	v_bfe_u32 v79, v54, 16, 1
	v_add3_u32 v54, v54, v79, s45
	v_bfe_u32 v80, v51, 16, 1
	s_waitcnt lgkmcnt(0)
	v_add_f32_e32 v44, v44, v45
	v_fmamk_f32 v44, v44, 0x3b000000, v194
	v_mul_f32_e32 v45, 0x4f800000, v44
	v_cmp_gt_f32_e32 vcc, s13, v44
	v_bfe_u32 v81, v50, 16, 1
	v_add3_u32 v50, v50, v81, s45
	v_cndmask_b32_e32 v48, v44, v45, vcc
	v_sqrt_f32_e32 v49, v48
	v_lshrrev_b32_e32 v44, 16, v53
	v_and_or_b32 v45, v46, s43, v44
	v_and_or_b32 v44, v54, s43, v47
	v_add_u32_e32 v46, -1, v49
	v_fma_f32 v47, -v46, v49, v48
	v_cmp_ge_f32_e64 s[0:1], 0, v47
	v_add_u32_e32 v47, 1, v49
	v_add3_u32 v51, v51, v80, s45
	v_cndmask_b32_e64 v46, v49, v46, s[0:1]
	v_fma_f32 v49, -v47, v49, v48
	v_cmp_lt_f32_e64 s[0:1], 0, v49
	v_lshrrev_b32_e32 v42, 16, v42
	v_lshrrev_b32_e32 v43, 16, v43
	v_cndmask_b32_e64 v46, v46, v47, s[0:1]
	v_mul_f32_e32 v47, 0x37800000, v46
	v_cndmask_b32_e32 v46, v46, v47, vcc
	v_cmp_class_f32_e32 vcc, v48, v195
	v_and_or_b32 v43, v51, s43, v43
	v_and_or_b32 v42, v50, s43, v42
	v_cndmask_b32_e32 v46, v46, v48, vcc
	v_div_scale_f32 v47, s[0:1], v46, v46, 1.0
	v_rcp_f32_e32 v48, v47
	global_store_dwordx4 v[38:39], v[42:45], off offset:1024
	s_waitcnt vmcnt(2)
	v_lshlrev_b32_e32 v49, 16, v31
	v_and_b32_e32 v51, 0xffff0000, v31
	v_fma_f32 v42, -v47, v48, 1.0
	v_fmac_f32_e32 v48, v42, v48
	v_div_scale_f32 v42, vcc, 1.0, v46, 1.0
	v_mul_f32_e32 v43, v42, v48
	v_fma_f32 v44, -v47, v43, v42
	v_fmac_f32_e32 v43, v44, v48
	v_fma_f32 v42, -v47, v43, v42
	v_div_fmas_f32 v42, v42, v48, v43
	v_lshlrev_b32_e32 v48, 16, v30
	v_and_b32_e32 v50, 0xffff0000, v30
	v_pk_mul_f32 v[30:31], v[48:49], v[48:49]
	v_pk_mul_f32 v[52:53], v[50:51], v[50:51]
	v_lshlrev_b32_e32 v55, 16, v33
	v_add_f32_e32 v30, v30, v52
	v_add_f32_e32 v30, v31, v30
	v_lshlrev_b32_e32 v54, 16, v32
	v_and_b32_e32 v57, 0xffff0000, v33
	v_add_f32_e32 v30, v53, v30
	v_and_b32_e32 v56, 0xffff0000, v32
	v_mov_b32_e32 v32, v57
	v_mov_b32_e32 v33, v55
	v_fmac_f32_e32 v30, v54, v54
	v_pk_mul_f32 v[32:33], v[32:33], v[32:33]
	v_fmac_f32_e32 v30, v56, v56
	v_div_fixup_f32 v42, v42, v46, 1.0
	v_add_f32_e32 v30, v33, v30
	v_pk_mul_f32 v[44:45], v[42:43], v[58:59] op_sel_hi:[0,1]
	v_pk_mul_f32 v[46:47], v[42:43], v[60:61] op_sel_hi:[0,1]
	v_add_f32_e32 v43, v32, v30
	ds_bpermute_b32 v52, v62, v43
	v_pk_mul_f32 v[32:33], v[42:43], v[34:35] op_sel_hi:[0,1]
	v_pk_mul_f32 v[34:35], v[42:43], v[36:37] op_sel_hi:[0,1]
	v_pk_mul_f32 v[30:31], v[6:7], v[46:47]
	v_pk_mul_f32 v[32:33], v[12:13], v[32:33]
	s_waitcnt lgkmcnt(0)
	v_add_f32_e32 v36, v43, v52
	ds_bpermute_b32 v37, v63, v36
	v_bfe_u32 v46, v31, 16, 1
	v_pk_mul_f32 v[34:35], v[10:11], v[34:35]
	v_bfe_u32 v47, v30, 16, 1
	v_add3_u32 v31, v31, v46, s45
	s_waitcnt lgkmcnt(0)
	v_add_f32_e32 v36, v36, v37
	ds_bpermute_b32 v37, v64, v36
	v_bfe_u32 v46, v32, 16, 1
	v_bfe_u32 v43, v34, 16, 1
	v_add3_u32 v30, v30, v47, s45
	v_bfe_u32 v47, v33, 16, 1
	s_waitcnt lgkmcnt(0)
	v_add_f32_e32 v36, v36, v37
	ds_bpermute_b32 v37, v65, v36
	v_add3_u32 v32, v32, v46, s45
	v_bfe_u32 v42, v35, 16, 1
	v_add3_u32 v34, v34, v43, s45
	v_add3_u32 v33, v33, v47, s45
	s_waitcnt lgkmcnt(0)
	v_add_f32_e32 v36, v36, v37
	ds_bpermute_b32 v37, v66, v36
	v_lshrrev_b32_e32 v32, 16, v32
	v_add3_u32 v35, v35, v42, s45
	v_lshrrev_b32_e32 v33, 16, v33
	v_and_or_b32 v32, v34, s43, v32
	s_waitcnt lgkmcnt(0)
	v_add_f32_e32 v36, v36, v37
	ds_bpermute_b32 v37, v67, v36
	v_and_or_b32 v33, v35, s43, v33
	v_pk_mul_f32 v[44:45], v[8:9], v[44:45]
	s_waitcnt lgkmcnt(0)
	v_add_f32_e32 v36, v36, v37
	v_fmamk_f32 v36, v36, 0x3b000000, v194
	v_mul_f32_e32 v37, 0x4f800000, v36
	v_cmp_gt_f32_e32 vcc, s13, v36
	v_bfe_u32 v42, v44, 16, 1
	v_bfe_u32 v43, v45, 16, 1
	v_cndmask_b32_e32 v36, v36, v37, vcc
	v_sqrt_f32_e32 v37, v36
	v_add3_u32 v43, v45, v43, s45
	v_add3_u32 v42, v44, v42, s45
	v_lshrrev_b32_e32 v42, 16, v42
	v_add_u32_e32 v34, -1, v37
	v_fma_f32 v35, -v34, v37, v36
	v_cmp_ge_f32_e64 s[0:1], 0, v35
	v_add_u32_e32 v35, 1, v37
	v_lshrrev_b32_e32 v43, 16, v43
	v_cndmask_b32_e64 v34, v37, v34, s[0:1]
	v_fma_f32 v37, -v35, v37, v36
	v_cmp_lt_f32_e64 s[0:1], 0, v37
	v_and_or_b32 v31, v31, s43, v43
	v_and_or_b32 v30, v30, s43, v42
	v_cndmask_b32_e64 v34, v34, v35, s[0:1]
	v_mul_f32_e32 v35, 0x37800000, v34
	v_cndmask_b32_e32 v34, v34, v35, vcc
	v_cmp_class_f32_e32 vcc, v36, v195
	global_store_dwordx4 v[38:39], v[30:33], off offset:2048
	s_nop 0
	v_cndmask_b32_e32 v34, v34, v36, vcc
	v_div_scale_f32 v35, s[0:1], v34, v34, 1.0
	v_rcp_f32_e32 v36, v35
	s_nop 0
	v_fma_f32 v30, -v35, v36, 1.0
	v_fmac_f32_e32 v36, v30, v36
	v_div_scale_f32 v30, vcc, 1.0, v34, 1.0
	v_mul_f32_e32 v31, v30, v36
	v_fma_f32 v32, -v35, v31, v30
	v_fmac_f32_e32 v31, v32, v36
	v_fma_f32 v30, -v35, v31, v30
	v_div_fmas_f32 v30, v30, v36, v31
	v_div_fixup_f32 v30, v30, v34, 1.0
	v_pk_mul_f32 v[32:33], v[30:31], v[48:49] op_sel_hi:[0,1]
	v_pk_mul_f32 v[34:35], v[30:31], v[50:51] op_sel_hi:[0,1]
	v_pk_mul_f32 v[36:37], v[30:31], v[54:55] op_sel_hi:[0,1]
	v_pk_mul_f32 v[30:31], v[30:31], v[56:57] op_sel_hi:[0,1]
	v_pk_mul_f32 v[34:35], v[40:41], v[34:35]
	v_pk_mul_f32 v[30:31], v[2:3], v[30:31]
	v_pk_mul_f32 v[32:33], v[0:1], v[32:33]
	v_pk_mul_f32 v[36:37], v[4:5], v[36:37]
	v_bfe_u32 v42, v31, 16, 1
	v_bfe_u32 v43, v30, 16, 1
	v_bfe_u32 v44, v35, 16, 1
	v_bfe_u32 v45, v34, 16, 1
	v_add3_u32 v34, v34, v45, s45
	v_add3_u32 v35, v35, v44, s45
	v_add3_u32 v30, v30, v43, s45
	v_add3_u32 v31, v31, v42, s45
	v_bfe_u32 v42, v32, 16, 1
	v_bfe_u32 v43, v33, 16, 1
	v_bfe_u32 v44, v36, 16, 1
	v_bfe_u32 v45, v37, 16, 1
	v_add3_u32 v37, v37, v45, s45
	v_add3_u32 v36, v36, v44, s45
	v_add3_u32 v33, v33, v43, s45
	v_add3_u32 v32, v32, v42, s45
	v_lshrrev_b32_e32 v42, 16, v32
	v_lshrrev_b32_e32 v43, 16, v33
	v_lshrrev_b32_e32 v32, 16, v36
	v_lshrrev_b32_e32 v33, 16, v37
	v_and_or_b32 v33, v31, s43, v33
	v_and_or_b32 v32, v30, s43, v32
	v_and_or_b32 v31, v35, s43, v43
	v_and_or_b32 v30, v34, s43, v42
	global_store_dwordx4 v[38:39], v[30:33], off offset:3072
	v_lshl_add_u64 v[38:39], v[38:39], 0, s[8:9]
	s_cbranch_scc1 .LBB0_467
